# second scalar pass on the P1/P3/P9 K-loops: next-tile select and pointer adds whose results are first needed one super-phase later moved from the SP1 load segment into SP1's MFMA block, dead s_mov_b64
# speedup vs baseline: 1.0094x; 1.0005x over previous
; #define PG8_STAGE(bufoff, gbase, voff) do { _Pragma("unroll") for (int _i = 0; _i < 2; ++_i) \
;         __builtin_amdgcn_global_load_lds((const unsigned*)((const char*)(gbase) + (voff)[_i]), (PG8_LAS unsigned*)(lds + (bufoff) + ldsw + _i * 8192), 16, 0, 0); } while (0)
; #define PG8_LDA(dst, b, h) do { _Pragma("unroll") for (int m = 0; m < 4; ++m) _Pragma("unroll") for (int k = 0; k < 2; ++k) dst[m][k] = *(const PG8_LAS bf16x8*)(lds + PG8_SA(b, h) + aoff + m * 2048 + k * 1024); } while (0)
; #define PG8_LDB(dst, b, h) do { _Pragma("unroll") for (int n = 0; n < 2; ++n) _Pragma("unroll") for (int k = 0; k < 2; ++k) dst[n][k] = *(const PG8_LAS bf16x8*)(lds + PG8_SB(b, h) + boff + n * 2048 + k * 1024); } while (0)
; #define PG8_MMA(ai, bj, At, Bt) do { __builtin_amdgcn_s_setprio(1); _Pragma("unroll") for (int m = 0; m < 4; ++m) _Pragma("unroll") for (int n = 0; n < 2; ++n) _Pragma("unroll") for (int k = 0; k < 2; ++k) \
;         acc[ai][bj][m][n] = __builtin_amdgcn_mfma_f32_16x16x32_bf16(Bt[n][k], At[m][k], acc[ai][bj][m][n], 0, 0, 0); __builtin_amdgcn_s_setprio(0); } while (0)
; #define PG8_WAIT_V(n) asm volatile("s_waitcnt vmcnt(" #n ")" ::: "memory")
; #define PG8_WAIT_L(n) asm volatile("s_waitcnt lgkmcnt(" #n ")" ::: "memory")
; #define PG8_BAR __builtin_amdgcn_s_barrier()
; template <class Epi, bool ALIGN_EPI, bool ABLK = false>
; __device__ __forceinline__ void gemm_phase(PG8_LAS unsigned char* lds, const Gemm g, const StaticOrder& S, const Epi& E) {
;     ...
;         for (int t = 0; t < nt; t += 2) {
;             const bool last = (t == nt - 2);
;             const char* a1 = cA + (size_t)(t + 1) * kstepA;
;             const char* a2 = last ? nA : cA + (size_t)(t + 2) * kstepA; const char* b2 = last ? nB : cB + (size_t)(t + 2) * kstepB;
;             const char* a3 = a2 + kstepA; const char* b3 = b2 + kstepB;
;             PG8_LDB(B0, 0, 0); PG8_LDB(B1, 0, 1); PG8_SCHED; PG8_LDA(At, 0, 0); PG8_STAGE(PG8_SA(1, 1), a1 + hstepA, voffA);
;             PG8_WAIT_V(8); PG8_WAIT_L(0); PG8_BAR; PG8_MMA(0, 0, At, B0); PG8_MMA(0, 1, At, B1); PG8_BAR; PG8_SCHED;
;             PG8_LDA(At, 0, 1); PG8_STAGE(PG8_SB(0, 0), b2, voffB); PG8_STAGE(PG8_SB(0, 1), b2 + hstepB, voffB); PG8_STAGE(PG8_SA(0, 0), a2, voffA);
;             PG8_WAIT_V(8); PG8_WAIT_L(0); PG8_BAR; PG8_MMA(1, 0, At, B0); PG8_MMA(1, 1, At, B1); PG8_BAR; PG8_SCHED;
.LBB0_402:
	ds_read_b128 v[132:135], v251
	ds_read_b128 v[136:139], v251 offset:1024
	ds_read_b128 v[140:143], v251 offset:2048
	ds_read_b128 v[186:189], v251 offset:3072
	ds_read_b128 v[190:193], v251 offset:16384
	ds_read_b128 v[194:197], v251 offset:17408
	ds_read_b128 v[198:201], v251 offset:18432
	ds_read_b128 v[202:205], v251 offset:19456
	s_add_i32 m0, s55, 0xc000
	ds_read_b128 v[206:209], v183
	ds_read_b128 v[210:213], v183 offset:1024
	ds_read_b128 v[214:217], v183 offset:2048
	ds_read_b128 v[218:221], v183 offset:3072
	ds_read_b128 v[222:225], v183 offset:4096
	ds_read_b128 v[226:229], v183 offset:5120
	ds_read_b128 v[230:233], v183 offset:6144
	ds_read_b128 v[234:237], v183 offset:7168
	global_load_lds_dwordx4 v249, s[82:83]
	s_add_i32 m0, s55, 0xe000
	s_nop 0
	global_load_lds_dwordx4 v250, s[82:83]
	s_waitcnt vmcnt(8)
	s_waitcnt lgkmcnt(0)
	s_barrier
	s_setprio 1
	s_waitcnt lgkmcnt(0)
	v_mfma_f32_16x16x32_bf16 v[126:129], v[132:135], v[206:209], v[126:129]
	v_mfma_f32_16x16x32_bf16 v[122:125], v[140:143], v[206:209], v[122:125]
	v_mfma_f32_16x16x32_bf16 v[118:121], v[132:135], v[214:217], v[118:121]
	v_mfma_f32_16x16x32_bf16 v[114:117], v[140:143], v[214:217], v[114:117]
	v_mfma_f32_16x16x32_bf16 v[110:113], v[132:135], v[222:225], v[110:113]
	v_mfma_f32_16x16x32_bf16 v[106:109], v[140:143], v[222:225], v[106:109]
	v_mfma_f32_16x16x32_bf16 v[102:105], v[132:135], v[230:233], v[102:105]
	v_mfma_f32_16x16x32_bf16 v[98:101], v[140:143], v[230:233], v[98:101]
	v_mfma_f32_16x16x32_bf16 v[126:129], v[136:139], v[210:213], v[126:129]
	v_mfma_f32_16x16x32_bf16 v[122:125], v[186:189], v[210:213], v[122:125]
	v_mfma_f32_16x16x32_bf16 v[118:121], v[136:139], v[218:221], v[118:121]
	v_mfma_f32_16x16x32_bf16 v[114:117], v[186:189], v[218:221], v[114:117]
	v_mfma_f32_16x16x32_bf16 v[110:113], v[136:139], v[226:229], v[110:113]
	v_mfma_f32_16x16x32_bf16 v[106:109], v[186:189], v[226:229], v[106:109]
	v_mfma_f32_16x16x32_bf16 v[102:105], v[136:139], v[234:237], v[102:105]
	v_mfma_f32_16x16x32_bf16 v[98:101], v[186:189], v[234:237], v[98:101]
	s_setprio 0
	s_setprio 1
	v_mfma_f32_16x16x32_bf16 v[94:97], v[190:193], v[206:209], v[94:97]
	s_add_i32 s71, s64, s9
	v_mfma_f32_16x16x32_bf16 v[90:93], v[198:201], v[206:209], v[90:93]
	s_mov_b32 m0, s71
	v_mfma_f32_16x16x32_bf16 v[86:89], v[190:193], v[214:217], v[86:89]
	s_add_u32 s48, s24, s46
	s_addc_u32 s49, s25, s47
	v_mfma_f32_16x16x32_bf16 v[82:85], v[198:201], v[214:217], v[82:85]
	s_cmp_eq_u32 s70, 12
	s_cselect_b32 s85, s41, s49
	v_mfma_f32_16x16x32_bf16 v[78:81], v[190:193], v[222:225], v[78:81]
	s_cselect_b32 s84, s66, s48
	s_cselect_b32 s49, s39, s69
	v_mfma_f32_16x16x32_bf16 v[74:77], v[198:201], v[222:225], v[74:77]
	s_cselect_b32 s48, s67, s68
	s_add_u32 s74, s48, 0x40000
	v_mfma_f32_16x16x32_bf16 v[70:73], v[190:193], v[230:233], v[70:73]
	s_addc_u32 s75, s49, 0
	v_mfma_f32_16x16x32_bf16 v[66:69], v[198:201], v[230:233], v[66:69]
	v_mfma_f32_16x16x32_bf16 v[94:97], v[194:197], v[210:213], v[94:97]
	v_mfma_f32_16x16x32_bf16 v[90:93], v[202:205], v[210:213], v[90:93]
	v_mfma_f32_16x16x32_bf16 v[86:89], v[194:197], v[218:221], v[86:89]
	v_mfma_f32_16x16x32_bf16 v[82:85], v[202:205], v[218:221], v[82:85]
	v_mfma_f32_16x16x32_bf16 v[78:81], v[194:197], v[226:229], v[78:81]
	v_mfma_f32_16x16x32_bf16 v[74:77], v[202:205], v[226:229], v[74:77]
	v_mfma_f32_16x16x32_bf16 v[70:73], v[194:197], v[234:237], v[70:73]
	v_mfma_f32_16x16x32_bf16 v[66:69], v[202:205], v[234:237], v[66:69]
	s_setprio 0
	s_barrier
	ds_read_b128 v[206:209], v183 offset:16384
	ds_read_b128 v[210:213], v183 offset:17408
	ds_read_b128 v[214:217], v183 offset:18432
	ds_read_b128 v[218:221], v183 offset:19456
	ds_read_b128 v[222:225], v183 offset:20480
	ds_read_b128 v[226:229], v183 offset:21504
	ds_read_b128 v[230:233], v183 offset:22528
	ds_read_b128 v[234:237], v183 offset:23552
	global_load_lds_dwordx4 v148, s[48:49]
	s_add_i32 m0, s71, 0x2000
	s_add_i32 s71, s65, s9
	global_load_lds_dwordx4 v150, s[48:49]
	s_mov_b32 m0, s71
	s_nop 0
	global_load_lds_dwordx4 v148, s[74:75]
	s_add_i32 m0, s71, 0x2000
	s_nop 0
	global_load_lds_dwordx4 v150, s[74:75]
	s_mov_b32 m0, s55
	s_mov_b64 s[72:73], 0x2000
	global_load_lds_dwordx4 v146, s[84:85]
	s_mov_b32 m0, s56
	s_nop 0
	global_load_lds_dwordx4 v244, s[84:85]
	s_waitcnt vmcnt(8)
	s_waitcnt lgkmcnt(0)
	s_barrier
	s_setprio 1
	s_waitcnt lgkmcnt(0)
	v_mfma_f32_16x16x32_bf16 v[62:65], v[132:135], v[206:209], v[62:65]
	v_mfma_f32_16x16x32_bf16 v[58:61], v[140:143], v[206:209], v[58:61]
	v_mfma_f32_16x16x32_bf16 v[54:57], v[132:135], v[214:217], v[54:57]
	v_mfma_f32_16x16x32_bf16 v[50:53], v[140:143], v[214:217], v[50:53]
	v_mfma_f32_16x16x32_bf16 v[46:49], v[132:135], v[222:225], v[46:49]
	v_mfma_f32_16x16x32_bf16 v[42:45], v[140:143], v[222:225], v[42:45]
	v_mfma_f32_16x16x32_bf16 v[38:41], v[132:135], v[230:233], v[38:41]
	v_mfma_f32_16x16x32_bf16 v[34:37], v[140:143], v[230:233], v[34:37]
	v_mfma_f32_16x16x32_bf16 v[62:65], v[136:139], v[210:213], v[62:65]
	v_mfma_f32_16x16x32_bf16 v[58:61], v[186:189], v[210:213], v[58:61]
	v_mfma_f32_16x16x32_bf16 v[54:57], v[136:139], v[218:221], v[54:57]
	v_mfma_f32_16x16x32_bf16 v[50:53], v[186:189], v[218:221], v[50:53]
	v_mfma_f32_16x16x32_bf16 v[46:49], v[136:139], v[226:229], v[46:49]
	v_mfma_f32_16x16x32_bf16 v[42:45], v[186:189], v[226:229], v[42:45]
	v_mfma_f32_16x16x32_bf16 v[38:41], v[136:139], v[234:237], v[38:41]
	v_mfma_f32_16x16x32_bf16 v[34:37], v[186:189], v[234:237], v[34:37]
	s_setprio 0
	s_setprio 1
	v_mfma_f32_16x16x32_bf16 v[30:33], v[190:193], v[206:209], v[30:33]
	s_add_i32 s71, 0, 0x18000
	v_mfma_f32_16x16x32_bf16 v[26:29], v[198:201], v[206:209], v[26:29]
	s_add_i32 s74, 0, 0x1c000
	v_mfma_f32_16x16x32_bf16 v[22:25], v[190:193], v[214:217], v[22:25]
	v_mfma_f32_16x16x32_bf16 v[18:21], v[198:201], v[214:217], v[18:21]
	v_mfma_f32_16x16x32_bf16 v[14:17], v[190:193], v[222:225], v[14:17]
	v_mfma_f32_16x16x32_bf16 v[10:13], v[198:201], v[222:225], v[10:13]
	v_mfma_f32_16x16x32_bf16 v[6:9], v[190:193], v[230:233], v[6:9]
	v_mfma_f32_16x16x32_bf16 v[2:5], v[198:201], v[230:233], v[2:5]
	v_mfma_f32_16x16x32_bf16 v[30:33], v[194:197], v[210:213], v[30:33]
	v_mfma_f32_16x16x32_bf16 v[26:29], v[202:205], v[210:213], v[26:29]
	v_mfma_f32_16x16x32_bf16 v[22:25], v[194:197], v[218:221], v[22:25]
	v_mfma_f32_16x16x32_bf16 v[18:21], v[202:205], v[218:221], v[18:21]
	v_mfma_f32_16x16x32_bf16 v[14:17], v[194:197], v[226:229], v[14:17]
	v_mfma_f32_16x16x32_bf16 v[10:13], v[202:205], v[226:229], v[10:13]
	v_mfma_f32_16x16x32_bf16 v[6:9], v[194:197], v[234:237], v[6:9]
	v_mfma_f32_16x16x32_bf16 v[2:5], v[202:205], v[234:237], v[2:5]
	s_setprio 0
	s_barrier
; #define PG8_STAGE(bufoff, gbase, voff) do { _Pragma("unroll") for (int _i = 0; _i < 2; ++_i) \
;         __builtin_amdgcn_global_load_lds((const unsigned*)((const char*)(gbase) + (voff)[_i]), (PG8_LAS unsigned*)(lds + (bufoff) + ldsw + _i * 8192), 16, 0, 0); } while (0)
; #define PG8_LDA(dst, b, h) do { _Pragma("unroll") for (int m = 0; m < 4; ++m) _Pragma("unroll") for (int k = 0; k < 2; ++k) dst[m][k] = *(const PG8_LAS bf16x8*)(lds + PG8_SA(b, h) + aoff + m * 2048 + k * 1024); } while (0)
; #define PG8_LDB(dst, b, h) do { _Pragma("unroll") for (int n = 0; n < 2; ++n) _Pragma("unroll") for (int k = 0; k < 2; ++k) dst[n][k] = *(const PG8_LAS bf16x8*)(lds + PG8_SB(b, h) + boff + n * 2048 + k * 1024); } while (0)
; #define PG8_MMA(ai, bj, At, Bt) do { __builtin_amdgcn_s_setprio(1); _Pragma("unroll") for (int m = 0; m < 4; ++m) _Pragma("unroll") for (int n = 0; n < 2; ++n) _Pragma("unroll") for (int k = 0; k < 2; ++k) \
;         acc[ai][bj][m][n] = __builtin_amdgcn_mfma_f32_16x16x32_bf16(Bt[n][k], At[m][k], acc[ai][bj][m][n], 0, 0, 0); __builtin_amdgcn_s_setprio(0); } while (0)
; #define PG8_WAIT_V(n) asm volatile("s_waitcnt vmcnt(" #n ")" ::: "memory")
; #define PG8_WAIT_L(n) asm volatile("s_waitcnt lgkmcnt(" #n ")" ::: "memory")
; #define PG8_BAR __builtin_amdgcn_s_barrier()
; #define PG8_SCHED __builtin_amdgcn_sched_barrier(0)
; template <class Epi, bool ALIGN_EPI, bool ABLK = false>
; __device__ __forceinline__ void gemm_phase(PG8_LAS unsigned char* lds, const Gemm g, const StaticOrder& S, const Epi& E) {
;     ...
;             PG8_LDB(B0, 1, 0); PG8_LDB(B1, 1, 1); PG8_SCHED; PG8_LDA(At, 1, 0); PG8_STAGE(PG8_SA(0, 1), a2 + hstepA, voffA);
;             PG8_WAIT_V(8); PG8_WAIT_L(0); PG8_BAR; PG8_MMA(0, 0, At, B0); PG8_MMA(0, 1, At, B1); PG8_BAR; PG8_SCHED;
;             PG8_LDA(At, 1, 1); PG8_STAGE(PG8_SB(1, 0), b3, voffB); PG8_STAGE(PG8_SB(1, 1), b3 + hstepB, voffB); PG8_STAGE(PG8_SA(1, 0), a3, voffA);
;             PG8_WAIT_V(8); PG8_WAIT_L(0); PG8_BAR; PG8_MMA(1, 0, At, B0); PG8_MMA(1, 1, At, B1); PG8_BAR; PG8_SCHED;
	ds_read_b128 v[132:135], v251 offset:32768
	ds_read_b128 v[136:139], v251 offset:33792
	ds_read_b128 v[140:143], v251 offset:34816
	ds_read_b128 v[186:189], v251 offset:35840
	ds_read_b128 v[190:193], v251 offset:49152
	ds_read_b128 v[194:197], v251 offset:50176
	ds_read_b128 v[198:201], v251 offset:51200
	ds_read_b128 v[202:205], v251 offset:52224
	s_mov_b32 m0, s57
	ds_read_b128 v[206:209], v183 offset:32768
	ds_read_b128 v[210:213], v183 offset:33792
	ds_read_b128 v[214:217], v183 offset:34816
	ds_read_b128 v[218:221], v183 offset:35840
	ds_read_b128 v[222:225], v183 offset:36864
	ds_read_b128 v[226:229], v183 offset:37888
	ds_read_b128 v[230:233], v183 offset:38912
	ds_read_b128 v[234:237], v183 offset:39936
	global_load_lds_dwordx4 v245, s[84:85]
	s_mov_b32 m0, s58
	s_nop 0
	global_load_lds_dwordx4 v246, s[84:85]
	s_waitcnt vmcnt(8)
	s_waitcnt lgkmcnt(0)
	s_barrier
	s_setprio 1
	s_waitcnt lgkmcnt(0)
	v_mfma_f32_16x16x32_bf16 v[126:129], v[132:135], v[206:209], v[126:129]
	v_mfma_f32_16x16x32_bf16 v[122:125], v[140:143], v[206:209], v[122:125]
	v_mfma_f32_16x16x32_bf16 v[118:121], v[132:135], v[214:217], v[118:121]
	v_mfma_f32_16x16x32_bf16 v[114:117], v[140:143], v[214:217], v[114:117]
	v_mfma_f32_16x16x32_bf16 v[110:113], v[132:135], v[222:225], v[110:113]
	v_mfma_f32_16x16x32_bf16 v[106:109], v[140:143], v[222:225], v[106:109]
	v_mfma_f32_16x16x32_bf16 v[102:105], v[132:135], v[230:233], v[102:105]
	v_mfma_f32_16x16x32_bf16 v[98:101], v[140:143], v[230:233], v[98:101]
	v_mfma_f32_16x16x32_bf16 v[126:129], v[136:139], v[210:213], v[126:129]
	v_mfma_f32_16x16x32_bf16 v[122:125], v[186:189], v[210:213], v[122:125]
	v_mfma_f32_16x16x32_bf16 v[118:121], v[136:139], v[218:221], v[118:121]
	v_mfma_f32_16x16x32_bf16 v[114:117], v[186:189], v[218:221], v[114:117]
	v_mfma_f32_16x16x32_bf16 v[110:113], v[136:139], v[226:229], v[110:113]
	v_mfma_f32_16x16x32_bf16 v[106:109], v[186:189], v[226:229], v[106:109]
	v_mfma_f32_16x16x32_bf16 v[102:105], v[136:139], v[234:237], v[102:105]
	v_mfma_f32_16x16x32_bf16 v[98:101], v[186:189], v[234:237], v[98:101]
	s_setprio 0
	s_setprio 1
	v_mfma_f32_16x16x32_bf16 v[94:97], v[190:193], v[206:209], v[94:97]
	s_add_i32 s71, s71, s9
	v_mfma_f32_16x16x32_bf16 v[90:93], v[198:201], v[206:209], v[90:93]
	s_add_u32 s86, s48, s28
	v_mfma_f32_16x16x32_bf16 v[86:89], v[190:193], v[214:217], v[86:89]
	s_addc_u32 s87, s49, s29
	v_mfma_f32_16x16x32_bf16 v[82:85], v[198:201], v[214:217], v[82:85]
	s_mov_b32 m0, s71
	v_mfma_f32_16x16x32_bf16 v[78:81], v[190:193], v[222:225], v[78:81]
	s_add_u32 s48, s48, 0x40080
	s_addc_u32 s49, s49, 0
	v_mfma_f32_16x16x32_bf16 v[74:77], v[198:201], v[222:225], v[74:77]
	v_mfma_f32_16x16x32_bf16 v[70:73], v[190:193], v[230:233], v[70:73]
	v_mfma_f32_16x16x32_bf16 v[66:69], v[198:201], v[230:233], v[66:69]
	v_mfma_f32_16x16x32_bf16 v[94:97], v[194:197], v[210:213], v[94:97]
	v_mfma_f32_16x16x32_bf16 v[90:93], v[202:205], v[210:213], v[90:93]
	v_mfma_f32_16x16x32_bf16 v[86:89], v[194:197], v[218:221], v[86:89]
	v_mfma_f32_16x16x32_bf16 v[82:85], v[202:205], v[218:221], v[82:85]
	v_mfma_f32_16x16x32_bf16 v[78:81], v[194:197], v[226:229], v[78:81]
	v_mfma_f32_16x16x32_bf16 v[74:77], v[202:205], v[226:229], v[74:77]
	v_mfma_f32_16x16x32_bf16 v[70:73], v[194:197], v[234:237], v[70:73]
	v_mfma_f32_16x16x32_bf16 v[66:69], v[202:205], v[234:237], v[66:69]
	s_setprio 0
	s_barrier
	ds_read_b128 v[206:209], v183 offset:49152
	ds_read_b128 v[210:213], v183 offset:50176
	ds_read_b128 v[214:217], v183 offset:51200
	ds_read_b128 v[218:221], v183 offset:52224
	ds_read_b128 v[222:225], v183 offset:53248
	ds_read_b128 v[226:229], v183 offset:54272
	ds_read_b128 v[230:233], v183 offset:55296
	ds_read_b128 v[234:237], v183 offset:56320
	global_load_lds_dwordx4 v148, s[86:87]
	s_add_i32 m0, s71, 0x2000
	s_add_i32 s71, s74, s9
	global_load_lds_dwordx4 v150, s[86:87]
	s_mov_b32 m0, s71
	s_nop 0
	global_load_lds_dwordx4 v148, s[48:49]
	s_add_i32 m0, s71, 0x2000
	s_nop 0
	global_load_lds_dwordx4 v150, s[48:49]
	s_mov_b32 m0, s59
	s_nop 0
	global_load_lds_dwordx4 v247, s[84:85]
	s_mov_b32 m0, s61
	s_nop 0
	global_load_lds_dwordx4 v248, s[84:85]
	s_waitcnt vmcnt(8)
	s_waitcnt lgkmcnt(0)
	s_barrier
	s_setprio 1
	s_waitcnt lgkmcnt(0)
	v_mfma_f32_16x16x32_bf16 v[62:65], v[132:135], v[206:209], v[62:65]
	v_mfma_f32_16x16x32_bf16 v[58:61], v[140:143], v[206:209], v[58:61]
	v_mfma_f32_16x16x32_bf16 v[54:57], v[132:135], v[214:217], v[54:57]
	v_mfma_f32_16x16x32_bf16 v[50:53], v[140:143], v[214:217], v[50:53]
	v_mfma_f32_16x16x32_bf16 v[46:49], v[132:135], v[222:225], v[46:49]
	v_mfma_f32_16x16x32_bf16 v[42:45], v[140:143], v[222:225], v[42:45]
	v_mfma_f32_16x16x32_bf16 v[38:41], v[132:135], v[230:233], v[38:41]
	v_mfma_f32_16x16x32_bf16 v[34:37], v[140:143], v[230:233], v[34:37]
	v_mfma_f32_16x16x32_bf16 v[62:65], v[136:139], v[210:213], v[62:65]
	v_mfma_f32_16x16x32_bf16 v[58:61], v[186:189], v[210:213], v[58:61]
	v_mfma_f32_16x16x32_bf16 v[54:57], v[136:139], v[218:221], v[54:57]
	v_mfma_f32_16x16x32_bf16 v[50:53], v[186:189], v[218:221], v[50:53]
	v_mfma_f32_16x16x32_bf16 v[46:49], v[136:139], v[226:229], v[46:49]
	v_mfma_f32_16x16x32_bf16 v[42:45], v[186:189], v[226:229], v[42:45]
	v_mfma_f32_16x16x32_bf16 v[38:41], v[136:139], v[234:237], v[38:41]
	v_mfma_f32_16x16x32_bf16 v[34:37], v[186:189], v[234:237], v[34:37]
	s_setprio 0
	s_setprio 1
	v_mfma_f32_16x16x32_bf16 v[30:33], v[190:193], v[206:209], v[30:33]
	s_add_i32 s70, s70, 2
	v_mfma_f32_16x16x32_bf16 v[26:29], v[198:201], v[206:209], v[26:29]
	s_add_u32 s68, s68, 0x100
	v_mfma_f32_16x16x32_bf16 v[22:25], v[190:193], v[214:217], v[22:25]
	s_addc_u32 s69, s69, 0
	v_mfma_f32_16x16x32_bf16 v[18:21], v[198:201], v[214:217], v[18:21]
	s_add_u32 s46, s46, 0x10000
	v_mfma_f32_16x16x32_bf16 v[14:17], v[190:193], v[222:225], v[14:17]
	s_addc_u32 s47, s47, 0
	v_mfma_f32_16x16x32_bf16 v[10:13], v[198:201], v[222:225], v[10:13]
	s_add_u32 s82, s82, 0x10000
	v_mfma_f32_16x16x32_bf16 v[6:9], v[190:193], v[230:233], v[6:9]
	s_addc_u32 s83, s83, 0
	v_mfma_f32_16x16x32_bf16 v[2:5], v[198:201], v[230:233], v[2:5]
	s_mov_b64 s[48:49], 0x10000
	v_mfma_f32_16x16x32_bf16 v[30:33], v[194:197], v[210:213], v[30:33]
	s_cmp_gt_u32 s70, 13
	v_mfma_f32_16x16x32_bf16 v[26:29], v[202:205], v[210:213], v[26:29]
	v_mfma_f32_16x16x32_bf16 v[22:25], v[194:197], v[218:221], v[22:25]
	v_mfma_f32_16x16x32_bf16 v[18:21], v[202:205], v[218:221], v[18:21]
	v_mfma_f32_16x16x32_bf16 v[14:17], v[194:197], v[226:229], v[14:17]
	v_mfma_f32_16x16x32_bf16 v[10:13], v[202:205], v[226:229], v[10:13]
	v_mfma_f32_16x16x32_bf16 v[6:9], v[194:197], v[234:237], v[6:9]
	v_mfma_f32_16x16x32_bf16 v[2:5], v[202:205], v[234:237], v[2:5]
	s_setprio 0
	s_barrier
	s_cbranch_scc0 .LBB0_402
	s_and_b64 vcc, exec, s[36:37]
	s_cbranch_vccz .LBB0_405
	s_barrier

; #define PG8_STAGE(bufoff, gbase, voff) do { _Pragma("unroll") for (int _i = 0; _i < 2; ++_i) \
;         __builtin_amdgcn_global_load_lds((const unsigned*)((const char*)(gbase) + (voff)[_i]), (PG8_LAS unsigned*)(lds + (bufoff) + ldsw + _i * 8192), 16, 0, 0); } while (0)
; #define PG8_LDA(dst, b, h) do { _Pragma("unroll") for (int m = 0; m < 4; ++m) _Pragma("unroll") for (int k = 0; k < 2; ++k) dst[m][k] = *(const PG8_LAS bf16x8*)(lds + PG8_SA(b, h) + aoff + m * 2048 + k * 1024); } while (0)
; #define PG8_LDB(dst, b, h) do { _Pragma("unroll") for (int n = 0; n < 2; ++n) _Pragma("unroll") for (int k = 0; k < 2; ++k) dst[n][k] = *(const PG8_LAS bf16x8*)(lds + PG8_SB(b, h) + boff + n * 2048 + k * 1024); } while (0)
; #define PG8_MMA(ai, bj, At, Bt) do { __builtin_amdgcn_s_setprio(1); _Pragma("unroll") for (int m = 0; m < 4; ++m) _Pragma("unroll") for (int n = 0; n < 2; ++n) _Pragma("unroll") for (int k = 0; k < 2; ++k) \
;         acc[ai][bj][m][n] = __builtin_amdgcn_mfma_f32_16x16x32_bf16(Bt[n][k], At[m][k], acc[ai][bj][m][n], 0, 0, 0); __builtin_amdgcn_s_setprio(0); } while (0)
; #define PG8_WAIT_V(n) asm volatile("s_waitcnt vmcnt(" #n ")" ::: "memory")
; #define PG8_WAIT_L(n) asm volatile("s_waitcnt lgkmcnt(" #n ")" ::: "memory")
; #define PG8_BAR __builtin_amdgcn_s_barrier()
; template <class Epi, bool ALIGN_EPI, bool ABLK = false>
; __device__ __forceinline__ void gemm_phase(PG8_LAS unsigned char* lds, const Gemm g, const StaticOrder& S, const Epi& E) {
;     ...
;         for (int t = 0; t < nt; t += 2) {
;             const bool last = (t == nt - 2);
;             const char* a1 = cA + (size_t)(t + 1) * kstepA;
;             const char* a2 = last ? nA : cA + (size_t)(t + 2) * kstepA; const char* b2 = last ? nB : cB + (size_t)(t + 2) * kstepB;
;             const char* a3 = a2 + kstepA; const char* b3 = b2 + kstepB;
;             PG8_LDB(B0, 0, 0); PG8_LDB(B1, 0, 1); PG8_SCHED; PG8_LDA(At, 0, 0); PG8_STAGE(PG8_SA(1, 1), a1 + hstepA, voffA);
;             PG8_WAIT_V(8); PG8_WAIT_L(0); PG8_BAR; PG8_MMA(0, 0, At, B0); PG8_MMA(0, 1, At, B1); PG8_BAR; PG8_SCHED;
;             PG8_LDA(At, 0, 1); PG8_STAGE(PG8_SB(0, 0), b2, voffB); PG8_STAGE(PG8_SB(0, 1), b2 + hstepB, voffB); PG8_STAGE(PG8_SA(0, 0), a2, voffA);
;             PG8_WAIT_V(8); PG8_WAIT_L(0); PG8_BAR; PG8_MMA(1, 0, At, B0); PG8_MMA(1, 1, At, B1); PG8_BAR; PG8_SCHED;
.LBB0_818:
	ds_read_b128 v[132:135], v153
	ds_read_b128 v[136:139], v153 offset:1024
	ds_read_b128 v[140:143], v153 offset:2048
	ds_read_b128 v[144:147], v153 offset:3072
	ds_read_b128 v[148:151], v153 offset:16384
	ds_read_b128 v[178:181], v153 offset:17408
	ds_read_b128 v[182:185], v153 offset:18432
	ds_read_b128 v[212:215], v153 offset:19456
	s_add_u32 s12, s38, s10
	s_addc_u32 s13, s39, s11
	s_sub_u32 s98, s12, 0x10000
	s_subb_u32 s99, s13, 0
	s_add_i32 m0, s35, 0xc000
	ds_read_b128 v[216:219], v205
	ds_read_b128 v[220:223], v205 offset:1024
	ds_read_b128 v[224:227], v205 offset:2048
	ds_read_b128 v[228:231], v205 offset:3072
	ds_read_b128 v[232:235], v205 offset:4096
	ds_read_b128 v[236:239], v205 offset:5120
	ds_read_b128 v[240:243], v205 offset:6144
	ds_read_b128 v[244:247], v205 offset:7168
	global_load_lds_dwordx4 v253, s[98:99]
	s_add_i32 m0, s35, 0xe000
	s_nop 0
	global_load_lds_dwordx4 v152, s[98:99]
	s_waitcnt vmcnt(8)
	s_waitcnt lgkmcnt(0)
	s_barrier
	s_setprio 1
	s_waitcnt lgkmcnt(0)
	v_mfma_f32_16x16x32_bf16 v[126:129], v[132:135], v[216:219], v[126:129]
	v_mfma_f32_16x16x32_bf16 v[122:125], v[140:143], v[216:219], v[122:125]
	v_mfma_f32_16x16x32_bf16 v[118:121], v[132:135], v[224:227], v[118:121]
	v_mfma_f32_16x16x32_bf16 v[114:117], v[140:143], v[224:227], v[114:117]
	v_mfma_f32_16x16x32_bf16 v[110:113], v[132:135], v[232:235], v[110:113]
	v_mfma_f32_16x16x32_bf16 v[106:109], v[140:143], v[232:235], v[106:109]
	v_mfma_f32_16x16x32_bf16 v[102:105], v[132:135], v[240:243], v[102:105]
	v_mfma_f32_16x16x32_bf16 v[98:101], v[140:143], v[240:243], v[98:101]
	v_mfma_f32_16x16x32_bf16 v[126:129], v[136:139], v[220:223], v[126:129]
	v_mfma_f32_16x16x32_bf16 v[122:125], v[144:147], v[220:223], v[122:125]
	v_mfma_f32_16x16x32_bf16 v[118:121], v[136:139], v[228:231], v[118:121]
	v_mfma_f32_16x16x32_bf16 v[114:117], v[144:147], v[228:231], v[114:117]
	v_mfma_f32_16x16x32_bf16 v[110:113], v[136:139], v[236:239], v[110:113]
	v_mfma_f32_16x16x32_bf16 v[106:109], v[144:147], v[236:239], v[106:109]
	v_mfma_f32_16x16x32_bf16 v[102:105], v[136:139], v[244:247], v[102:105]
	v_mfma_f32_16x16x32_bf16 v[98:101], v[144:147], v[244:247], v[98:101]
	s_setprio 0
	s_setprio 1
	v_mfma_f32_16x16x32_bf16 v[94:97], v[148:151], v[216:219], v[94:97]
	s_add_i32 s68, s42, s31
	v_mfma_f32_16x16x32_bf16 v[90:93], v[182:185], v[216:219], v[90:93]
	s_mov_b32 m0, s68
	v_mfma_f32_16x16x32_bf16 v[86:89], v[148:151], v[224:227], v[86:89]
	s_cmp_eq_u32 s65, 12
	s_cselect_b32 s101, s33, s13
	v_mfma_f32_16x16x32_bf16 v[82:85], v[182:185], v[224:227], v[82:85]
	s_cselect_b32 s100, s57, s12
	s_cselect_b32 s13, s55, s64
	v_mfma_f32_16x16x32_bf16 v[78:81], v[148:151], v[232:235], v[78:81]
	s_cselect_b32 s12, s62, s63
	v_mfma_f32_16x16x32_bf16 v[74:77], v[182:185], v[232:235], v[74:77]
	v_mfma_f32_16x16x32_bf16 v[70:73], v[148:151], v[240:243], v[70:73]
	v_mfma_f32_16x16x32_bf16 v[66:69], v[182:185], v[240:243], v[66:69]
	v_mfma_f32_16x16x32_bf16 v[94:97], v[178:181], v[220:223], v[94:97]
	v_mfma_f32_16x16x32_bf16 v[90:93], v[212:215], v[220:223], v[90:93]
	v_mfma_f32_16x16x32_bf16 v[86:89], v[178:181], v[228:231], v[86:89]
	v_mfma_f32_16x16x32_bf16 v[82:85], v[212:215], v[228:231], v[82:85]
	v_mfma_f32_16x16x32_bf16 v[78:81], v[178:181], v[236:239], v[78:81]
	v_mfma_f32_16x16x32_bf16 v[74:77], v[212:215], v[236:239], v[74:77]
	v_mfma_f32_16x16x32_bf16 v[70:73], v[178:181], v[244:247], v[70:73]
	v_mfma_f32_16x16x32_bf16 v[66:69], v[212:215], v[244:247], v[66:69]
	s_setprio 0
	s_barrier
	ds_read_b128 v[216:219], v205 offset:16384
	ds_read_b128 v[220:223], v205 offset:17408
	ds_read_b128 v[224:227], v205 offset:18432
	ds_read_b128 v[228:231], v205 offset:19456
	ds_read_b128 v[232:235], v205 offset:20480
	ds_read_b128 v[236:239], v205 offset:21504
	ds_read_b128 v[240:243], v205 offset:22528
	ds_read_b128 v[244:247], v205 offset:23552
	global_load_lds_dwordx4 v156, s[12:13]
	s_add_i32 m0, s68, 0x2000
	s_add_u32 s68, s12, 0x40000
	s_addc_u32 s69, s13, 0
	s_add_i32 s70, s43, s31
	global_load_lds_dwordx4 v158, s[12:13]
	s_mov_b32 m0, s70
	s_nop 0
	global_load_lds_dwordx4 v156, s[68:69]
	s_add_i32 m0, s70, 0x2000
	s_nop 0
	global_load_lds_dwordx4 v158, s[68:69]
	s_mov_b32 m0, s35
	s_mov_b64 s[66:67], 0x2000
	global_load_lds_dwordx4 v154, s[100:101]
	s_mov_b32 m0, s18
	s_nop 0
	global_load_lds_dwordx4 v248, s[100:101]
	s_waitcnt vmcnt(8)
	s_waitcnt lgkmcnt(0)
	s_barrier
	s_setprio 1
	s_waitcnt lgkmcnt(0)
	v_mfma_f32_16x16x32_bf16 v[62:65], v[132:135], v[216:219], v[62:65]
	v_mfma_f32_16x16x32_bf16 v[58:61], v[140:143], v[216:219], v[58:61]
	v_mfma_f32_16x16x32_bf16 v[54:57], v[132:135], v[224:227], v[54:57]
	v_mfma_f32_16x16x32_bf16 v[50:53], v[140:143], v[224:227], v[50:53]
	v_mfma_f32_16x16x32_bf16 v[46:49], v[132:135], v[232:235], v[46:49]
	v_mfma_f32_16x16x32_bf16 v[42:45], v[140:143], v[232:235], v[42:45]
	v_mfma_f32_16x16x32_bf16 v[38:41], v[132:135], v[240:243], v[38:41]
	v_mfma_f32_16x16x32_bf16 v[34:37], v[140:143], v[240:243], v[34:37]
	v_mfma_f32_16x16x32_bf16 v[62:65], v[136:139], v[220:223], v[62:65]
	v_mfma_f32_16x16x32_bf16 v[58:61], v[144:147], v[220:223], v[58:61]
	v_mfma_f32_16x16x32_bf16 v[54:57], v[136:139], v[228:231], v[54:57]
	v_mfma_f32_16x16x32_bf16 v[50:53], v[144:147], v[228:231], v[50:53]
	v_mfma_f32_16x16x32_bf16 v[46:49], v[136:139], v[236:239], v[46:49]
	v_mfma_f32_16x16x32_bf16 v[42:45], v[144:147], v[236:239], v[42:45]
	v_mfma_f32_16x16x32_bf16 v[38:41], v[136:139], v[244:247], v[38:41]
	v_mfma_f32_16x16x32_bf16 v[34:37], v[144:147], v[244:247], v[34:37]
	s_setprio 0
	s_setprio 1
	v_mfma_f32_16x16x32_bf16 v[30:33], v[148:151], v[216:219], v[30:33]
	s_add_i32 s68, 0, 0x18000
	v_mfma_f32_16x16x32_bf16 v[26:29], v[182:185], v[216:219], v[26:29]
	s_add_i32 s69, 0, 0x1c000
	v_mfma_f32_16x16x32_bf16 v[22:25], v[148:151], v[224:227], v[22:25]
	v_mfma_f32_16x16x32_bf16 v[18:21], v[182:185], v[224:227], v[18:21]
	v_mfma_f32_16x16x32_bf16 v[14:17], v[148:151], v[232:235], v[14:17]
	v_mfma_f32_16x16x32_bf16 v[10:13], v[182:185], v[232:235], v[10:13]
	v_mfma_f32_16x16x32_bf16 v[6:9], v[148:151], v[240:243], v[6:9]
	v_mfma_f32_16x16x32_bf16 v[2:5], v[182:185], v[240:243], v[2:5]
	v_mfma_f32_16x16x32_bf16 v[30:33], v[178:181], v[220:223], v[30:33]
	v_mfma_f32_16x16x32_bf16 v[26:29], v[212:215], v[220:223], v[26:29]
	v_mfma_f32_16x16x32_bf16 v[22:25], v[178:181], v[228:231], v[22:25]
	v_mfma_f32_16x16x32_bf16 v[18:21], v[212:215], v[228:231], v[18:21]
	v_mfma_f32_16x16x32_bf16 v[14:17], v[178:181], v[236:239], v[14:17]
	v_mfma_f32_16x16x32_bf16 v[10:13], v[212:215], v[236:239], v[10:13]
	v_mfma_f32_16x16x32_bf16 v[6:9], v[178:181], v[244:247], v[6:9]
	v_mfma_f32_16x16x32_bf16 v[2:5], v[212:215], v[244:247], v[2:5]
	s_setprio 0
	s_barrier
; #define PG8_STAGE(bufoff, gbase, voff) do { _Pragma("unroll") for (int _i = 0; _i < 2; ++_i) \
;         __builtin_amdgcn_global_load_lds((const unsigned*)((const char*)(gbase) + (voff)[_i]), (PG8_LAS unsigned*)(lds + (bufoff) + ldsw + _i * 8192), 16, 0, 0); } while (0)
; #define PG8_LDA(dst, b, h) do { _Pragma("unroll") for (int m = 0; m < 4; ++m) _Pragma("unroll") for (int k = 0; k < 2; ++k) dst[m][k] = *(const PG8_LAS bf16x8*)(lds + PG8_SA(b, h) + aoff + m * 2048 + k * 1024); } while (0)
; #define PG8_LDB(dst, b, h) do { _Pragma("unroll") for (int n = 0; n < 2; ++n) _Pragma("unroll") for (int k = 0; k < 2; ++k) dst[n][k] = *(const PG8_LAS bf16x8*)(lds + PG8_SB(b, h) + boff + n * 2048 + k * 1024); } while (0)
; #define PG8_MMA(ai, bj, At, Bt) do { __builtin_amdgcn_s_setprio(1); _Pragma("unroll") for (int m = 0; m < 4; ++m) _Pragma("unroll") for (int n = 0; n < 2; ++n) _Pragma("unroll") for (int k = 0; k < 2; ++k) \
;         acc[ai][bj][m][n] = __builtin_amdgcn_mfma_f32_16x16x32_bf16(Bt[n][k], At[m][k], acc[ai][bj][m][n], 0, 0, 0); __builtin_amdgcn_s_setprio(0); } while (0)
; #define PG8_WAIT_V(n) asm volatile("s_waitcnt vmcnt(" #n ")" ::: "memory")
; #define PG8_WAIT_L(n) asm volatile("s_waitcnt lgkmcnt(" #n ")" ::: "memory")
; #define PG8_BAR __builtin_amdgcn_s_barrier()
; #define PG8_SCHED __builtin_amdgcn_sched_barrier(0)
; template <class Epi, bool ALIGN_EPI, bool ABLK = false>
; __device__ __forceinline__ void gemm_phase(PG8_LAS unsigned char* lds, const Gemm g, const StaticOrder& S, const Epi& E) {
;     ...
;             PG8_LDB(B0, 1, 0); PG8_LDB(B1, 1, 1); PG8_SCHED; PG8_LDA(At, 1, 0); PG8_STAGE(PG8_SA(0, 1), a2 + hstepA, voffA);
;             PG8_WAIT_V(8); PG8_WAIT_L(0); PG8_BAR; PG8_MMA(0, 0, At, B0); PG8_MMA(0, 1, At, B1); PG8_BAR; PG8_SCHED;
;             PG8_LDA(At, 1, 1); PG8_STAGE(PG8_SB(1, 0), b3, voffB); PG8_STAGE(PG8_SB(1, 1), b3 + hstepB, voffB); PG8_STAGE(PG8_SA(1, 0), a3, voffA);
;             PG8_WAIT_V(8); PG8_WAIT_L(0); PG8_BAR; PG8_MMA(1, 0, At, B0); PG8_MMA(1, 1, At, B1); PG8_BAR; PG8_SCHED;
	ds_read_b128 v[132:135], v153 offset:32768
	ds_read_b128 v[136:139], v153 offset:33792
	ds_read_b128 v[140:143], v153 offset:34816
	ds_read_b128 v[144:147], v153 offset:35840
	ds_read_b128 v[148:151], v153 offset:49152
	ds_read_b128 v[178:181], v153 offset:50176
	ds_read_b128 v[182:185], v153 offset:51200
	ds_read_b128 v[212:215], v153 offset:52224
	s_mov_b32 m0, s28
	ds_read_b128 v[216:219], v205 offset:32768
	ds_read_b128 v[220:223], v205 offset:33792
	ds_read_b128 v[224:227], v205 offset:34816
	ds_read_b128 v[228:231], v205 offset:35840
	ds_read_b128 v[232:235], v205 offset:36864
	ds_read_b128 v[236:239], v205 offset:37888
	ds_read_b128 v[240:243], v205 offset:38912
	ds_read_b128 v[244:247], v205 offset:39936
	global_load_lds_dwordx4 v249, s[100:101]
	s_mov_b32 m0, s29
	s_nop 0
	global_load_lds_dwordx4 v250, s[100:101]
	s_waitcnt vmcnt(8)
	s_waitcnt lgkmcnt(0)
	s_barrier
	s_setprio 1
	s_waitcnt lgkmcnt(0)
	v_mfma_f32_16x16x32_bf16 v[126:129], v[132:135], v[216:219], v[126:129]
	v_mfma_f32_16x16x32_bf16 v[122:125], v[140:143], v[216:219], v[122:125]
	v_mfma_f32_16x16x32_bf16 v[118:121], v[132:135], v[224:227], v[118:121]
	v_mfma_f32_16x16x32_bf16 v[114:117], v[140:143], v[224:227], v[114:117]
	v_mfma_f32_16x16x32_bf16 v[110:113], v[132:135], v[232:235], v[110:113]
	v_mfma_f32_16x16x32_bf16 v[106:109], v[140:143], v[232:235], v[106:109]
	v_mfma_f32_16x16x32_bf16 v[102:105], v[132:135], v[240:243], v[102:105]
	v_mfma_f32_16x16x32_bf16 v[98:101], v[140:143], v[240:243], v[98:101]
	v_mfma_f32_16x16x32_bf16 v[126:129], v[136:139], v[220:223], v[126:129]
	v_mfma_f32_16x16x32_bf16 v[122:125], v[144:147], v[220:223], v[122:125]
	v_mfma_f32_16x16x32_bf16 v[118:121], v[136:139], v[228:231], v[118:121]
	v_mfma_f32_16x16x32_bf16 v[114:117], v[144:147], v[228:231], v[114:117]
	v_mfma_f32_16x16x32_bf16 v[110:113], v[136:139], v[236:239], v[110:113]
	v_mfma_f32_16x16x32_bf16 v[106:109], v[144:147], v[236:239], v[106:109]
	v_mfma_f32_16x16x32_bf16 v[102:105], v[136:139], v[244:247], v[102:105]
	v_mfma_f32_16x16x32_bf16 v[98:101], v[144:147], v[244:247], v[98:101]
	s_setprio 0
	s_setprio 1
	v_mfma_f32_16x16x32_bf16 v[94:97], v[148:151], v[216:219], v[94:97]
	s_add_i32 s66, s68, s31
	v_mfma_f32_16x16x32_bf16 v[90:93], v[182:185], v[216:219], v[90:93]
	s_add_u32 s12, s12, s46
	v_mfma_f32_16x16x32_bf16 v[86:89], v[148:151], v[224:227], v[86:89]
	s_addc_u32 s13, s13, s47
	v_mfma_f32_16x16x32_bf16 v[82:85], v[182:185], v[224:227], v[82:85]
	s_mov_b32 m0, s66
	v_mfma_f32_16x16x32_bf16 v[78:81], v[148:151], v[232:235], v[78:81]
	v_mfma_f32_16x16x32_bf16 v[74:77], v[182:185], v[232:235], v[74:77]
	v_mfma_f32_16x16x32_bf16 v[70:73], v[148:151], v[240:243], v[70:73]
	v_mfma_f32_16x16x32_bf16 v[66:69], v[182:185], v[240:243], v[66:69]
	v_mfma_f32_16x16x32_bf16 v[94:97], v[178:181], v[220:223], v[94:97]
	v_mfma_f32_16x16x32_bf16 v[90:93], v[212:215], v[220:223], v[90:93]
	v_mfma_f32_16x16x32_bf16 v[86:89], v[178:181], v[228:231], v[86:89]
	v_mfma_f32_16x16x32_bf16 v[82:85], v[212:215], v[228:231], v[82:85]
	v_mfma_f32_16x16x32_bf16 v[78:81], v[178:181], v[236:239], v[78:81]
	v_mfma_f32_16x16x32_bf16 v[74:77], v[212:215], v[236:239], v[74:77]
	v_mfma_f32_16x16x32_bf16 v[70:73], v[178:181], v[244:247], v[70:73]
	v_mfma_f32_16x16x32_bf16 v[66:69], v[212:215], v[244:247], v[66:69]
	s_setprio 0
	s_barrier
	ds_read_b128 v[216:219], v205 offset:49152
	ds_read_b128 v[220:223], v205 offset:50176
	ds_read_b128 v[224:227], v205 offset:51200
	ds_read_b128 v[228:231], v205 offset:52224
	ds_read_b128 v[232:235], v205 offset:53248
	ds_read_b128 v[236:239], v205 offset:54272
	ds_read_b128 v[240:243], v205 offset:55296
	ds_read_b128 v[244:247], v205 offset:56320
	global_load_lds_dwordx4 v156, s[12:13]
	s_add_i32 m0, s66, 0x2000
	s_add_i32 s66, s69, s31
	global_load_lds_dwordx4 v158, s[12:13]
	s_add_u32 s12, s12, 0x40000
	s_addc_u32 s13, s13, 0
	s_mov_b32 m0, s66
	s_nop 0
	global_load_lds_dwordx4 v156, s[12:13]
	s_add_i32 m0, s66, 0x2000
	s_nop 0
	global_load_lds_dwordx4 v158, s[12:13]
	s_mov_b32 m0, s0
	s_nop 0
	global_load_lds_dwordx4 v251, s[100:101]
	s_mov_b32 m0, s1
	s_nop 0
	global_load_lds_dwordx4 v252, s[100:101]
	s_waitcnt vmcnt(8)
	s_waitcnt lgkmcnt(0)
	s_barrier
	s_setprio 1
	s_waitcnt lgkmcnt(0)
	v_mfma_f32_16x16x32_bf16 v[62:65], v[132:135], v[216:219], v[62:65]
	v_mfma_f32_16x16x32_bf16 v[58:61], v[140:143], v[216:219], v[58:61]
	v_mfma_f32_16x16x32_bf16 v[54:57], v[132:135], v[224:227], v[54:57]
	v_mfma_f32_16x16x32_bf16 v[50:53], v[140:143], v[224:227], v[50:53]
	v_mfma_f32_16x16x32_bf16 v[46:49], v[132:135], v[232:235], v[46:49]
	v_mfma_f32_16x16x32_bf16 v[42:45], v[140:143], v[232:235], v[42:45]
	v_mfma_f32_16x16x32_bf16 v[38:41], v[132:135], v[240:243], v[38:41]
	v_mfma_f32_16x16x32_bf16 v[34:37], v[140:143], v[240:243], v[34:37]
	v_mfma_f32_16x16x32_bf16 v[62:65], v[136:139], v[220:223], v[62:65]
	v_mfma_f32_16x16x32_bf16 v[58:61], v[144:147], v[220:223], v[58:61]
	v_mfma_f32_16x16x32_bf16 v[54:57], v[136:139], v[228:231], v[54:57]
	v_mfma_f32_16x16x32_bf16 v[50:53], v[144:147], v[228:231], v[50:53]
	v_mfma_f32_16x16x32_bf16 v[46:49], v[136:139], v[236:239], v[46:49]
	v_mfma_f32_16x16x32_bf16 v[42:45], v[144:147], v[236:239], v[42:45]
	v_mfma_f32_16x16x32_bf16 v[38:41], v[136:139], v[244:247], v[38:41]
	v_mfma_f32_16x16x32_bf16 v[34:37], v[144:147], v[244:247], v[34:37]
	s_setprio 0
	s_setprio 1
	v_mfma_f32_16x16x32_bf16 v[30:33], v[148:151], v[216:219], v[30:33]
	s_add_i32 s65, s65, 2
	v_mfma_f32_16x16x32_bf16 v[26:29], v[182:185], v[216:219], v[26:29]
	s_add_u32 s63, s63, 0x100
	v_mfma_f32_16x16x32_bf16 v[22:25], v[148:151], v[224:227], v[22:25]
	s_addc_u32 s64, s64, 0
	v_mfma_f32_16x16x32_bf16 v[18:21], v[182:185], v[224:227], v[18:21]
	s_add_u32 s10, s10, 0x10000
	v_mfma_f32_16x16x32_bf16 v[14:17], v[148:151], v[232:235], v[14:17]
	s_addc_u32 s11, s11, 0
	v_mfma_f32_16x16x32_bf16 v[10:13], v[182:185], v[232:235], v[10:13]
	s_mov_b64 s[12:13], 0x10000
	v_mfma_f32_16x16x32_bf16 v[6:9], v[148:151], v[240:243], v[6:9]
	s_cmp_gt_u32 s65, 13
	v_mfma_f32_16x16x32_bf16 v[2:5], v[182:185], v[240:243], v[2:5]
	v_mfma_f32_16x16x32_bf16 v[30:33], v[178:181], v[220:223], v[30:33]
	v_mfma_f32_16x16x32_bf16 v[26:29], v[212:215], v[220:223], v[26:29]
	v_mfma_f32_16x16x32_bf16 v[22:25], v[178:181], v[228:231], v[22:25]
	v_mfma_f32_16x16x32_bf16 v[18:21], v[212:215], v[228:231], v[18:21]
	v_mfma_f32_16x16x32_bf16 v[14:17], v[178:181], v[236:239], v[14:17]
	v_mfma_f32_16x16x32_bf16 v[10:13], v[212:215], v[236:239], v[10:13]
	v_mfma_f32_16x16x32_bf16 v[6:9], v[178:181], v[244:247], v[6:9]
	v_mfma_f32_16x16x32_bf16 v[2:5], v[212:215], v[244:247], v[2:5]
	s_setprio 0
	s_barrier
	s_cbranch_scc0 .LBB0_818
	s_and_b64 vcc, exec, s[52:53]
	s_cbranch_vccz .LBB0_821
	s_barrier

; #define PG8_STAGE(bufoff, gbase, voff) do { _Pragma("unroll") for (int _i = 0; _i < 2; ++_i) \
;         __builtin_amdgcn_global_load_lds((const unsigned*)((const char*)(gbase) + (voff)[_i]), (PG8_LAS unsigned*)(lds + (bufoff) + ldsw + _i * 8192), 16, 0, 0); } while (0)
; #define PG8_LDA(dst, b, h) do { _Pragma("unroll") for (int m = 0; m < 4; ++m) _Pragma("unroll") for (int k = 0; k < 2; ++k) dst[m][k] = *(const PG8_LAS bf16x8*)(lds + PG8_SA(b, h) + aoff + m * 2048 + k * 1024); } while (0)
; #define PG8_LDB(dst, b, h) do { _Pragma("unroll") for (int n = 0; n < 2; ++n) _Pragma("unroll") for (int k = 0; k < 2; ++k) dst[n][k] = *(const PG8_LAS bf16x8*)(lds + PG8_SB(b, h) + boff + n * 2048 + k * 1024); } while (0)
; #define PG8_MMA(ai, bj, At, Bt) do { __builtin_amdgcn_s_setprio(1); _Pragma("unroll") for (int m = 0; m < 4; ++m) _Pragma("unroll") for (int n = 0; n < 2; ++n) _Pragma("unroll") for (int k = 0; k < 2; ++k) \
;         acc[ai][bj][m][n] = __builtin_amdgcn_mfma_f32_16x16x32_bf16(Bt[n][k], At[m][k], acc[ai][bj][m][n], 0, 0, 0); __builtin_amdgcn_s_setprio(0); } while (0)
; #define PG8_WAIT_V(n) asm volatile("s_waitcnt vmcnt(" #n ")" ::: "memory")
; #define PG8_WAIT_L(n) asm volatile("s_waitcnt lgkmcnt(" #n ")" ::: "memory")
; #define PG8_BAR __builtin_amdgcn_s_barrier()
; template <class Epi, bool ALIGN_EPI, bool ABLK = false>
; __device__ __forceinline__ void gemm_phase(PG8_LAS unsigned char* lds, const Gemm g, const StaticOrder& S, const Epi& E) {
;     ...
;         for (int t = 0; t < nt; t += 2) {
;             const bool last = (t == nt - 2);
;             const char* a1 = cA + (size_t)(t + 1) * kstepA;
;             const char* a2 = last ? nA : cA + (size_t)(t + 2) * kstepA; const char* b2 = last ? nB : cB + (size_t)(t + 2) * kstepB;
;             const char* a3 = a2 + kstepA; const char* b3 = b2 + kstepB;
;             PG8_LDB(B0, 0, 0); PG8_LDB(B1, 0, 1); PG8_SCHED; PG8_LDA(At, 0, 0); PG8_STAGE(PG8_SA(1, 1), a1 + hstepA, voffA);
;             PG8_WAIT_V(8); PG8_WAIT_L(0); PG8_BAR; PG8_MMA(0, 0, At, B0); PG8_MMA(0, 1, At, B1); PG8_BAR; PG8_SCHED;
;             PG8_LDA(At, 0, 1); PG8_STAGE(PG8_SB(0, 0), b2, voffB); PG8_STAGE(PG8_SB(0, 1), b2 + hstepB, voffB); PG8_STAGE(PG8_SA(0, 0), a2, voffA);
;             PG8_WAIT_V(8); PG8_WAIT_L(0); PG8_BAR; PG8_MMA(1, 0, At, B0); PG8_MMA(1, 1, At, B1); PG8_BAR; PG8_SCHED;
.LBB0_2495:
	ds_read_b128 v[132:135], v251
	ds_read_b128 v[178:181], v251 offset:1024
	ds_read_b128 v[182:185], v251 offset:2048
	ds_read_b128 v[186:189], v251 offset:3072
	ds_read_b128 v[190:193], v251 offset:16384
	ds_read_b128 v[194:197], v251 offset:17408
	ds_read_b128 v[198:201], v251 offset:18432
	ds_read_b128 v[202:205], v251 offset:19456
	s_add_u32 s60, s24, s58
	s_addc_u32 s61, s25, s59
	s_sub_u32 s98, s60, 0x10000
	s_subb_u32 s99, s61, 0
	s_add_i32 m0, s66, 0xc000
	ds_read_b128 v[206:209], v176
	ds_read_b128 v[210:213], v176 offset:1024
	ds_read_b128 v[214:217], v176 offset:2048
	ds_read_b128 v[218:221], v176 offset:3072
	ds_read_b128 v[222:225], v176 offset:4096
	ds_read_b128 v[226:229], v176 offset:5120
	ds_read_b128 v[230:233], v176 offset:6144
	ds_read_b128 v[234:237], v176 offset:7168
	global_load_lds_dwordx4 v249, s[98:99]
	s_add_i32 m0, s66, 0xe000
	s_nop 0
	global_load_lds_dwordx4 v250, s[98:99]
	s_waitcnt vmcnt(8)
	s_waitcnt lgkmcnt(0)
	s_barrier
	s_setprio 1
	s_waitcnt lgkmcnt(0)
	v_mfma_f32_16x16x32_bf16 v[126:129], v[132:135], v[206:209], v[126:129]
	v_mfma_f32_16x16x32_bf16 v[122:125], v[182:185], v[206:209], v[122:125]
	v_mfma_f32_16x16x32_bf16 v[118:121], v[132:135], v[214:217], v[118:121]
	v_mfma_f32_16x16x32_bf16 v[114:117], v[182:185], v[214:217], v[114:117]
	v_mfma_f32_16x16x32_bf16 v[110:113], v[132:135], v[222:225], v[110:113]
	v_mfma_f32_16x16x32_bf16 v[106:109], v[182:185], v[222:225], v[106:109]
	v_mfma_f32_16x16x32_bf16 v[102:105], v[132:135], v[230:233], v[102:105]
	v_mfma_f32_16x16x32_bf16 v[98:101], v[182:185], v[230:233], v[98:101]
	v_mfma_f32_16x16x32_bf16 v[126:129], v[178:181], v[210:213], v[126:129]
	v_mfma_f32_16x16x32_bf16 v[122:125], v[186:189], v[210:213], v[122:125]
	v_mfma_f32_16x16x32_bf16 v[118:121], v[178:181], v[218:221], v[118:121]
	v_mfma_f32_16x16x32_bf16 v[114:117], v[186:189], v[218:221], v[114:117]
	v_mfma_f32_16x16x32_bf16 v[110:113], v[178:181], v[226:229], v[110:113]
	v_mfma_f32_16x16x32_bf16 v[106:109], v[186:189], v[226:229], v[106:109]
	v_mfma_f32_16x16x32_bf16 v[102:105], v[178:181], v[234:237], v[102:105]
	v_mfma_f32_16x16x32_bf16 v[98:101], v[186:189], v[234:237], v[98:101]
	s_setprio 0
	s_setprio 1
	v_mfma_f32_16x16x32_bf16 v[94:97], v[190:193], v[206:209], v[94:97]
	s_add_i32 s86, s75, s9
	v_mfma_f32_16x16x32_bf16 v[90:93], v[198:201], v[206:209], v[90:93]
	s_mov_b32 m0, s86
	v_mfma_f32_16x16x32_bf16 v[86:89], v[190:193], v[214:217], v[86:89]
	s_cmp_eq_u32 s83, 12
	s_cselect_b32 s101, s53, s61
	v_mfma_f32_16x16x32_bf16 v[82:85], v[198:201], v[214:217], v[82:85]
	s_cselect_b32 s100, s79, s60
	s_cselect_b32 s61, s51, s82
	v_mfma_f32_16x16x32_bf16 v[78:81], v[190:193], v[222:225], v[78:81]
	s_cselect_b32 s60, s80, s81
	v_mfma_f32_16x16x32_bf16 v[74:77], v[198:201], v[222:225], v[74:77]
	v_mfma_f32_16x16x32_bf16 v[70:73], v[190:193], v[230:233], v[70:73]
	v_mfma_f32_16x16x32_bf16 v[66:69], v[198:201], v[230:233], v[66:69]
	v_mfma_f32_16x16x32_bf16 v[94:97], v[194:197], v[210:213], v[94:97]
	v_mfma_f32_16x16x32_bf16 v[90:93], v[202:205], v[210:213], v[90:93]
	v_mfma_f32_16x16x32_bf16 v[86:89], v[194:197], v[218:221], v[86:89]
	v_mfma_f32_16x16x32_bf16 v[82:85], v[202:205], v[218:221], v[82:85]
	v_mfma_f32_16x16x32_bf16 v[78:81], v[194:197], v[226:229], v[78:81]
	v_mfma_f32_16x16x32_bf16 v[74:77], v[202:205], v[226:229], v[74:77]
	v_mfma_f32_16x16x32_bf16 v[70:73], v[194:197], v[234:237], v[70:73]
	v_mfma_f32_16x16x32_bf16 v[66:69], v[202:205], v[234:237], v[66:69]
	s_setprio 0
	s_barrier
	ds_read_b128 v[206:209], v176 offset:16384
	ds_read_b128 v[210:213], v176 offset:17408
	ds_read_b128 v[214:217], v176 offset:18432
	ds_read_b128 v[218:221], v176 offset:19456
	ds_read_b128 v[222:225], v176 offset:20480
	ds_read_b128 v[226:229], v176 offset:21504
	ds_read_b128 v[230:233], v176 offset:22528
	ds_read_b128 v[234:237], v176 offset:23552
	global_load_lds_dwordx4 v140, s[60:61]
	s_add_i32 m0, s86, 0x2000
	s_add_u32 s86, s60, 0x40000
	s_addc_u32 s87, s61, 0
	s_add_i32 s88, s76, s9
	global_load_lds_dwordx4 v142, s[60:61]
	s_mov_b32 m0, s88
	s_nop 0
	global_load_lds_dwordx4 v140, s[86:87]
	s_add_i32 m0, s88, 0x2000
	s_nop 0
	global_load_lds_dwordx4 v142, s[86:87]
	s_mov_b32 m0, s66
	s_nop 0
	global_load_lds_dwordx4 v138, s[100:101]
	s_mov_b32 m0, s67
	s_nop 0
	global_load_lds_dwordx4 v244, s[100:101]
	s_waitcnt vmcnt(8)
	s_waitcnt lgkmcnt(0)
	s_barrier
	s_setprio 1
	s_waitcnt lgkmcnt(0)
	v_mfma_f32_16x16x32_bf16 v[62:65], v[132:135], v[206:209], v[62:65]
	v_mfma_f32_16x16x32_bf16 v[58:61], v[182:185], v[206:209], v[58:61]
	v_mfma_f32_16x16x32_bf16 v[54:57], v[132:135], v[214:217], v[54:57]
	v_mfma_f32_16x16x32_bf16 v[50:53], v[182:185], v[214:217], v[50:53]
	v_mfma_f32_16x16x32_bf16 v[46:49], v[132:135], v[222:225], v[46:49]
	v_mfma_f32_16x16x32_bf16 v[42:45], v[182:185], v[222:225], v[42:45]
	v_mfma_f32_16x16x32_bf16 v[38:41], v[132:135], v[230:233], v[38:41]
	v_mfma_f32_16x16x32_bf16 v[34:37], v[182:185], v[230:233], v[34:37]
	v_mfma_f32_16x16x32_bf16 v[62:65], v[178:181], v[210:213], v[62:65]
	v_mfma_f32_16x16x32_bf16 v[58:61], v[186:189], v[210:213], v[58:61]
	v_mfma_f32_16x16x32_bf16 v[54:57], v[178:181], v[218:221], v[54:57]
	v_mfma_f32_16x16x32_bf16 v[50:53], v[186:189], v[218:221], v[50:53]
	v_mfma_f32_16x16x32_bf16 v[46:49], v[178:181], v[226:229], v[46:49]
	v_mfma_f32_16x16x32_bf16 v[42:45], v[186:189], v[226:229], v[42:45]
	v_mfma_f32_16x16x32_bf16 v[38:41], v[178:181], v[234:237], v[38:41]
	v_mfma_f32_16x16x32_bf16 v[34:37], v[186:189], v[234:237], v[34:37]
	s_setprio 0
	s_setprio 1
	v_mfma_f32_16x16x32_bf16 v[30:33], v[190:193], v[206:209], v[30:33]
	s_add_i32 s84, 0, 0x18000
	v_mfma_f32_16x16x32_bf16 v[26:29], v[198:201], v[206:209], v[26:29]
	s_add_i32 s85, 0, 0x1c000
	v_mfma_f32_16x16x32_bf16 v[22:25], v[190:193], v[214:217], v[22:25]
	v_mfma_f32_16x16x32_bf16 v[18:21], v[198:201], v[214:217], v[18:21]
	v_mfma_f32_16x16x32_bf16 v[14:17], v[190:193], v[222:225], v[14:17]
	v_mfma_f32_16x16x32_bf16 v[10:13], v[198:201], v[222:225], v[10:13]
	v_mfma_f32_16x16x32_bf16 v[6:9], v[190:193], v[230:233], v[6:9]
	v_mfma_f32_16x16x32_bf16 v[2:5], v[198:201], v[230:233], v[2:5]
	v_mfma_f32_16x16x32_bf16 v[30:33], v[194:197], v[210:213], v[30:33]
	v_mfma_f32_16x16x32_bf16 v[26:29], v[202:205], v[210:213], v[26:29]
	v_mfma_f32_16x16x32_bf16 v[22:25], v[194:197], v[218:221], v[22:25]
	v_mfma_f32_16x16x32_bf16 v[18:21], v[202:205], v[218:221], v[18:21]
	v_mfma_f32_16x16x32_bf16 v[14:17], v[194:197], v[226:229], v[14:17]
	v_mfma_f32_16x16x32_bf16 v[10:13], v[202:205], v[226:229], v[10:13]
	v_mfma_f32_16x16x32_bf16 v[6:9], v[194:197], v[234:237], v[6:9]
	v_mfma_f32_16x16x32_bf16 v[2:5], v[202:205], v[234:237], v[2:5]
	s_setprio 0
	s_barrier
; #define PG8_STAGE(bufoff, gbase, voff) do { _Pragma("unroll") for (int _i = 0; _i < 2; ++_i) \
;         __builtin_amdgcn_global_load_lds((const unsigned*)((const char*)(gbase) + (voff)[_i]), (PG8_LAS unsigned*)(lds + (bufoff) + ldsw + _i * 8192), 16, 0, 0); } while (0)
; #define PG8_LDA(dst, b, h) do { _Pragma("unroll") for (int m = 0; m < 4; ++m) _Pragma("unroll") for (int k = 0; k < 2; ++k) dst[m][k] = *(const PG8_LAS bf16x8*)(lds + PG8_SA(b, h) + aoff + m * 2048 + k * 1024); } while (0)
; #define PG8_LDB(dst, b, h) do { _Pragma("unroll") for (int n = 0; n < 2; ++n) _Pragma("unroll") for (int k = 0; k < 2; ++k) dst[n][k] = *(const PG8_LAS bf16x8*)(lds + PG8_SB(b, h) + boff + n * 2048 + k * 1024); } while (0)
; #define PG8_MMA(ai, bj, At, Bt) do { __builtin_amdgcn_s_setprio(1); _Pragma("unroll") for (int m = 0; m < 4; ++m) _Pragma("unroll") for (int n = 0; n < 2; ++n) _Pragma("unroll") for (int k = 0; k < 2; ++k) \
;         acc[ai][bj][m][n] = __builtin_amdgcn_mfma_f32_16x16x32_bf16(Bt[n][k], At[m][k], acc[ai][bj][m][n], 0, 0, 0); __builtin_amdgcn_s_setprio(0); } while (0)
; #define PG8_WAIT_V(n) asm volatile("s_waitcnt vmcnt(" #n ")" ::: "memory")
; #define PG8_WAIT_L(n) asm volatile("s_waitcnt lgkmcnt(" #n ")" ::: "memory")
; #define PG8_BAR __builtin_amdgcn_s_barrier()
; #define PG8_SCHED __builtin_amdgcn_sched_barrier(0)
; template <class Epi, bool ALIGN_EPI, bool ABLK = false>
; __device__ __forceinline__ void gemm_phase(PG8_LAS unsigned char* lds, const Gemm g, const StaticOrder& S, const Epi& E) {
;     ...
;             PG8_LDB(B0, 1, 0); PG8_LDB(B1, 1, 1); PG8_SCHED; PG8_LDA(At, 1, 0); PG8_STAGE(PG8_SA(0, 1), a2 + hstepA, voffA);
;             PG8_WAIT_V(8); PG8_WAIT_L(0); PG8_BAR; PG8_MMA(0, 0, At, B0); PG8_MMA(0, 1, At, B1); PG8_BAR; PG8_SCHED;
;             PG8_LDA(At, 1, 1); PG8_STAGE(PG8_SB(1, 0), b3, voffB); PG8_STAGE(PG8_SB(1, 1), b3 + hstepB, voffB); PG8_STAGE(PG8_SA(1, 0), a3, voffA);
;             PG8_WAIT_V(8); PG8_WAIT_L(0); PG8_BAR; PG8_MMA(1, 0, At, B0); PG8_MMA(1, 1, At, B1); PG8_BAR; PG8_SCHED;
	ds_read_b128 v[132:135], v251 offset:32768
	ds_read_b128 v[178:181], v251 offset:33792
	ds_read_b128 v[182:185], v251 offset:34816
	ds_read_b128 v[186:189], v251 offset:35840
	ds_read_b128 v[190:193], v251 offset:49152
	ds_read_b128 v[194:197], v251 offset:50176
	ds_read_b128 v[198:201], v251 offset:51200
	ds_read_b128 v[202:205], v251 offset:52224
	s_mov_b32 m0, s68
	ds_read_b128 v[206:209], v176 offset:32768
	ds_read_b128 v[210:213], v176 offset:33792
	ds_read_b128 v[214:217], v176 offset:34816
	ds_read_b128 v[218:221], v176 offset:35840
	ds_read_b128 v[222:225], v176 offset:36864
	ds_read_b128 v[226:229], v176 offset:37888
	ds_read_b128 v[230:233], v176 offset:38912
	ds_read_b128 v[234:237], v176 offset:39936
	global_load_lds_dwordx4 v245, s[100:101]
	s_mov_b32 m0, s69
	s_nop 0
	global_load_lds_dwordx4 v246, s[100:101]
	s_waitcnt vmcnt(8)
	s_waitcnt lgkmcnt(0)
	s_barrier
	s_setprio 1
	s_waitcnt lgkmcnt(0)
	v_mfma_f32_16x16x32_bf16 v[126:129], v[132:135], v[206:209], v[126:129]
	v_mfma_f32_16x16x32_bf16 v[122:125], v[182:185], v[206:209], v[122:125]
	v_mfma_f32_16x16x32_bf16 v[118:121], v[132:135], v[214:217], v[118:121]
	v_mfma_f32_16x16x32_bf16 v[114:117], v[182:185], v[214:217], v[114:117]
	v_mfma_f32_16x16x32_bf16 v[110:113], v[132:135], v[222:225], v[110:113]
	v_mfma_f32_16x16x32_bf16 v[106:109], v[182:185], v[222:225], v[106:109]
	v_mfma_f32_16x16x32_bf16 v[102:105], v[132:135], v[230:233], v[102:105]
	v_mfma_f32_16x16x32_bf16 v[98:101], v[182:185], v[230:233], v[98:101]
	v_mfma_f32_16x16x32_bf16 v[126:129], v[178:181], v[210:213], v[126:129]
	v_mfma_f32_16x16x32_bf16 v[122:125], v[186:189], v[210:213], v[122:125]
	v_mfma_f32_16x16x32_bf16 v[118:121], v[178:181], v[218:221], v[118:121]
	v_mfma_f32_16x16x32_bf16 v[114:117], v[186:189], v[218:221], v[114:117]
	v_mfma_f32_16x16x32_bf16 v[110:113], v[178:181], v[226:229], v[110:113]
	v_mfma_f32_16x16x32_bf16 v[106:109], v[186:189], v[226:229], v[106:109]
	v_mfma_f32_16x16x32_bf16 v[102:105], v[178:181], v[234:237], v[102:105]
	v_mfma_f32_16x16x32_bf16 v[98:101], v[186:189], v[234:237], v[98:101]
	s_setprio 0
	s_setprio 1
	v_mfma_f32_16x16x32_bf16 v[94:97], v[190:193], v[206:209], v[94:97]
	s_add_i32 s84, s84, s9
	v_mfma_f32_16x16x32_bf16 v[90:93], v[198:201], v[206:209], v[90:93]
	s_add_u32 s60, s60, s28
	v_mfma_f32_16x16x32_bf16 v[86:89], v[190:193], v[214:217], v[86:89]
	s_addc_u32 s61, s61, s29
	v_mfma_f32_16x16x32_bf16 v[82:85], v[198:201], v[214:217], v[82:85]
	s_mov_b32 m0, s84
	v_mfma_f32_16x16x32_bf16 v[78:81], v[190:193], v[222:225], v[78:81]
	v_mfma_f32_16x16x32_bf16 v[74:77], v[198:201], v[222:225], v[74:77]
	v_mfma_f32_16x16x32_bf16 v[70:73], v[190:193], v[230:233], v[70:73]
	v_mfma_f32_16x16x32_bf16 v[66:69], v[198:201], v[230:233], v[66:69]
	v_mfma_f32_16x16x32_bf16 v[94:97], v[194:197], v[210:213], v[94:97]
	v_mfma_f32_16x16x32_bf16 v[90:93], v[202:205], v[210:213], v[90:93]
	v_mfma_f32_16x16x32_bf16 v[86:89], v[194:197], v[218:221], v[86:89]
	v_mfma_f32_16x16x32_bf16 v[82:85], v[202:205], v[218:221], v[82:85]
	v_mfma_f32_16x16x32_bf16 v[78:81], v[194:197], v[226:229], v[78:81]
	v_mfma_f32_16x16x32_bf16 v[74:77], v[202:205], v[226:229], v[74:77]
	v_mfma_f32_16x16x32_bf16 v[70:73], v[194:197], v[234:237], v[70:73]
	v_mfma_f32_16x16x32_bf16 v[66:69], v[202:205], v[234:237], v[66:69]
	s_setprio 0
	s_barrier
	ds_read_b128 v[206:209], v176 offset:49152
	ds_read_b128 v[210:213], v176 offset:50176
	ds_read_b128 v[214:217], v176 offset:51200
	ds_read_b128 v[218:221], v176 offset:52224
	ds_read_b128 v[222:225], v176 offset:53248
	ds_read_b128 v[226:229], v176 offset:54272
	ds_read_b128 v[230:233], v176 offset:55296
	ds_read_b128 v[234:237], v176 offset:56320
	global_load_lds_dwordx4 v140, s[60:61]
	s_add_i32 m0, s84, 0x2000
	s_add_i32 s84, s85, s9
	global_load_lds_dwordx4 v142, s[60:61]
	s_add_u32 s60, s60, 0x40000
	s_addc_u32 s61, s61, 0
	s_mov_b32 m0, s84
	s_nop 0
	global_load_lds_dwordx4 v140, s[60:61]
	s_add_i32 m0, s84, 0x2000
	s_nop 0
	global_load_lds_dwordx4 v142, s[60:61]
	s_mov_b32 m0, s70
	s_nop 0
	global_load_lds_dwordx4 v247, s[100:101]
	s_mov_b32 m0, s72
	s_nop 0
	global_load_lds_dwordx4 v248, s[100:101]
	s_waitcnt vmcnt(8)
	s_waitcnt lgkmcnt(0)
	s_barrier
	s_setprio 1
	s_waitcnt lgkmcnt(0)
	v_mfma_f32_16x16x32_bf16 v[62:65], v[132:135], v[206:209], v[62:65]
	v_mfma_f32_16x16x32_bf16 v[58:61], v[182:185], v[206:209], v[58:61]
	v_mfma_f32_16x16x32_bf16 v[54:57], v[132:135], v[214:217], v[54:57]
	v_mfma_f32_16x16x32_bf16 v[50:53], v[182:185], v[214:217], v[50:53]
	v_mfma_f32_16x16x32_bf16 v[46:49], v[132:135], v[222:225], v[46:49]
	v_mfma_f32_16x16x32_bf16 v[42:45], v[182:185], v[222:225], v[42:45]
	v_mfma_f32_16x16x32_bf16 v[38:41], v[132:135], v[230:233], v[38:41]
	v_mfma_f32_16x16x32_bf16 v[34:37], v[182:185], v[230:233], v[34:37]
	v_mfma_f32_16x16x32_bf16 v[62:65], v[178:181], v[210:213], v[62:65]
	v_mfma_f32_16x16x32_bf16 v[58:61], v[186:189], v[210:213], v[58:61]
	v_mfma_f32_16x16x32_bf16 v[54:57], v[178:181], v[218:221], v[54:57]
	v_mfma_f32_16x16x32_bf16 v[50:53], v[186:189], v[218:221], v[50:53]
	v_mfma_f32_16x16x32_bf16 v[46:49], v[178:181], v[226:229], v[46:49]
	v_mfma_f32_16x16x32_bf16 v[42:45], v[186:189], v[226:229], v[42:45]
	v_mfma_f32_16x16x32_bf16 v[38:41], v[178:181], v[234:237], v[38:41]
	v_mfma_f32_16x16x32_bf16 v[34:37], v[186:189], v[234:237], v[34:37]
	s_setprio 0
	s_setprio 1
	v_mfma_f32_16x16x32_bf16 v[30:33], v[190:193], v[206:209], v[30:33]
	s_add_i32 s83, s83, 2
	v_mfma_f32_16x16x32_bf16 v[26:29], v[198:201], v[206:209], v[26:29]
	s_add_u32 s81, s81, 0x100
	v_mfma_f32_16x16x32_bf16 v[22:25], v[190:193], v[214:217], v[22:25]
	s_addc_u32 s82, s82, 0
	v_mfma_f32_16x16x32_bf16 v[18:21], v[198:201], v[214:217], v[18:21]
	s_add_u32 s58, s58, 0x10000
	v_mfma_f32_16x16x32_bf16 v[14:17], v[190:193], v[222:225], v[14:17]
	s_addc_u32 s59, s59, 0
	v_mfma_f32_16x16x32_bf16 v[10:13], v[198:201], v[222:225], v[10:13]
	s_cmp_gt_u32 s83, 13
	v_mfma_f32_16x16x32_bf16 v[6:9], v[190:193], v[230:233], v[6:9]
	v_mfma_f32_16x16x32_bf16 v[2:5], v[198:201], v[230:233], v[2:5]
	v_mfma_f32_16x16x32_bf16 v[30:33], v[194:197], v[210:213], v[30:33]
	v_mfma_f32_16x16x32_bf16 v[26:29], v[202:205], v[210:213], v[26:29]
	v_mfma_f32_16x16x32_bf16 v[22:25], v[194:197], v[218:221], v[22:25]
	v_mfma_f32_16x16x32_bf16 v[18:21], v[202:205], v[218:221], v[18:21]
	v_mfma_f32_16x16x32_bf16 v[14:17], v[194:197], v[226:229], v[14:17]
	v_mfma_f32_16x16x32_bf16 v[10:13], v[202:205], v[226:229], v[10:13]
	v_mfma_f32_16x16x32_bf16 v[6:9], v[194:197], v[234:237], v[6:9]
	v_mfma_f32_16x16x32_bf16 v[2:5], v[202:205], v[234:237], v[2:5]
	s_setprio 0
	s_barrier
	s_cbranch_scc0 .LBB0_2495
	s_and_b64 vcc, exec, s[36:37]
	s_cbranch_vccz .LBB0_2498
	s_barrier
